# static s_setprio 1 for waves 0-3 (other half than v055) over each GEMM phase, per-MFMA-group priority flips deleted; on top of the barrier poll change
# baseline (speedup 1.0000x reference)
; #define PG8_LAS __attribute__((address_space(3)))
; template <class Epi, class Sched, bool ALIGN_EPI = false, bool SP2 = false>
; __device__ __forceinline__ void gemm_phase(PG8_LAS unsigned char* lds, const Gemm g, const Sched& S, const Epi& E, const int tid) {
;     const int wid = __builtin_amdgcn_readfirstlane(tid >> 6), lane = tid & 63, wr = wid >> 2, wc = wid & 3, fr = lane & 15, fq = lane >> 4;
.LBB0_75:
	v_readfirstlane_b32 s98, v158
	s_nop 3
	s_lshr_b32 s98, s98, 6
	s_cmp_lt_u32 s98, 4
	s_cbranch_scc0 .Lprio_skip_0
	s_setprio 1

; #define PG8_LAS __attribute__((address_space(3)))
; template <class Epi, class Sched, bool ALIGN_EPI = false, bool SP2 = false>
; __device__ __forceinline__ void gemm_phase(PG8_LAS unsigned char* lds, const Gemm g, const Sched& S, const Epi& E, const int tid) {
;     const int wid = __builtin_amdgcn_readfirstlane(tid >> 6), lane = tid & 63, wr = wid >> 2, wc = wid & 3, fr = lane & 15, fq = lane >> 4;
.LBB0_476:
	s_or_b64 exec, exec, s[2:3]
	s_mov_b64 s[2:3], -1
	s_and_b64 vcc, exec, s[94:95]
	s_waitcnt lgkmcnt(0)
	s_barrier
	v_readfirstlane_b32 s98, v158
	s_nop 3
	s_lshr_b32 s98, s98, 6
	s_cmp_lt_u32 s98, 4
	s_cbranch_scc0 .Lprio_skip_1
	s_setprio 1

; #define PG8_LAS __attribute__((address_space(3)))
; template <class Epi, class Sched, bool ALIGN_EPI = false, bool SP2 = false>
; __device__ __forceinline__ void gemm_phase(PG8_LAS unsigned char* lds, const Gemm g, const Sched& S, const Epi& E, const int tid) {
;     const int wid = __builtin_amdgcn_readfirstlane(tid >> 6), lane = tid & 63, wr = wid >> 2, wc = wid & 3, fr = lane & 15, fq = lane >> 4;
.LBB0_619:
	s_or_b64 exec, exec, s[2:3]
	s_waitcnt lgkmcnt(0)
	s_barrier
	v_readfirstlane_b32 s98, v158
	s_nop 3
	s_lshr_b32 s98, s98, 6
	s_cmp_lt_u32 s98, 4
	s_cbranch_scc0 .Lprio_skip_2
	s_setprio 1
